# FNet s1/s2 unit loops: first-unit vmcnt waits no longer force the previous unit's stores each unit; s2 end-of-unit waits counted (vmcnt 5/4 when mb != 4)
# speedup vs baseline: 1.0016x; 1.0016x over previous
; #define GAS __attribute__((address_space(1)))
; #define LAS __attribute__((address_space(3)))
; DI void s1_pipe8(const Frame& F, const bf16* UC, bf16* T, int u0, const bf16* Mx  ) {
;     constexpr int TILE = 128 * 144;
;     const int l15 = F.lane & 15, l4 = F.lane >> 4, q = l15 >> 2, pp = l15 & 3;
;     const int kt = F.wave & 3, cp = F.wave >> 2;
;     bf16x8 mcs[2], msn[2];
; #pragma unroll
;     for (int kk = 0; kk < 2; ++kk) { mcs[kk] = ld_frag_g(Mx + (size_t)(kt * 16 + l15) * 64 + kk * 32 + 8 * l4); msn[kk] = ld_frag_g(Mx + (size_t)(64 + kt * 16 + l15) * 64 + kk * 32 + 8 * l4); }
;     ...
;     v4u pre[2];
; #pragma unroll
;     for (int i = 0; i < 2; ++i) { const int p = F.tid + 512 * i; pre[i] = *(const GAS v4u*)(S1_ROW(u0, p >> 3) + (p & 7) * 8); }
; #pragma unroll
;     for (int i = 0; i < 2; ++i) { const int p = F.tid + 512 * i; *(LAS v4u*)(F.lds + (p >> 3) * 144 + (p & 7) * 16) = pre[i]; }
;     __syncthreads();
.LBB0_359:
	s_lshl_b32 s4, s13, 13
	s_and_b32 s10, s4, 0xfc000
	v_lshl_add_u64 v[4:5], v[50:51], 0, s[10:11]
	v_lshl_add_u64 v[4:5], v[46:47], 1, v[4:5]
	s_mov_b64 s[4:5], 0x2000
	v_lshl_add_u64 v[8:9], v[4:5], 0, s[4:5]
	s_lshl_b32 s4, s13, 5
	s_and_b32 s4, s4, 0xfffff000
	s_bfe_u32 s5, s13, 0x60001
	s_or_b32 s18, s5, s4
	s_ashr_i32 s19, s18, 31
	v_mov_b32_e32 v7, s19
	v_or_b32_e32 v6, s18, v52
	v_lshlrev_b64 v[6:7], 12, v[6:7]
	s_lshl_b32 s4, s13, 11
	v_lshl_add_u64 v[6:7], s[76:77], 0, v[6:7]
	s_and_b32 s10, s4, 0x800
	v_lshl_add_u64 v[6:7], v[6:7], 0, s[10:11]
	v_add_co_u32_e32 v10, vcc, 0x2000, v4
	v_lshl_add_u64 v[6:7], v[6:7], 0, v[2:3]
	v_lshl_add_u64 v[12:13], v[54:55], 1, v[6:7]
	v_lshl_add_u64 v[6:7], v[56:57], 1, v[6:7]
	v_addc_co_u32_e32 v11, vcc, 0, v5, vcc
	global_load_dwordx4 v[20:23], v[12:13], off
	global_load_dwordx4 v[24:27], v[6:7], off
	s_nop 0
	global_load_dwordx4 v[12:15], v[4:5], off
	s_nop 0
	global_load_dwordx4 v[4:7], v[4:5], off offset:64
	s_nop 0
	global_load_dwordx4 v[16:19], v[10:11], off
	s_nop 0
	global_load_dwordx4 v[8:11], v[8:9], off offset:64
	s_mov_b32 s20, 0
	s_mov_b32 s21, s17
	s_mov_b32 s22, s16
	s_mov_b32 s24, s14
	s_mov_b32 s23, s9
	s_waitcnt vmcnt(5)
	ds_write_b128 v67, v[20:23]
	s_waitcnt vmcnt(4)
	ds_write_b128 v68, v[24:27]
	s_waitcnt vmcnt(0) lgkmcnt(0)
	s_barrier
	s_branch .LBB0_361

; #define GAS __attribute__((address_space(1)))
; #define LAS __attribute__((address_space(3)))
; DI unsigned pk2(float lo, float hi) { f32x2_t v = {lo, hi}; bf16x2_t b = __builtin_convertvector(v, bf16x2_t); return __builtin_bit_cast(unsigned, b); }
; DI s16x4 vtr(const LAS unsigned char* p) { return __builtin_bit_cast(s16x4, __builtin_amdgcn_ds_read_tr16_b64_v4i16((LAS s16x4*)p)); }
; DI void s1_pipe8(const Frame& F, const bf16* UC, bf16* T, int u0, const bf16* Mx  ) {
;     ...
;     for (int k = 0; k < 8; ++k) {
;         LAS unsigned char* D = F.lds + (k & 1) * TILE;
;         const int u = u0 + k;
;         if (k + 1 < 8) {
; #pragma unroll
;             for (int i = 0; i < 2; ++i) { const int p = F.tid + 512 * i; pre[i] = *(const GAS v4u*)(S1_ROW(u + 1, p >> 3) + (p & 7) * 8); } }
;         const int b = u >> 10, n2 = (u >> 4) & 63, g = (u >> 2) & 3, mb = u & 3;
;         bf16* Tb = T + ((size_t)(b * SEQ + n2) + (size_t)(kt * 16 + l15) * 64) * 4096 + g * 1024 + mb * 64;
; #pragma unroll
;         for (int i = 0; i < 2; ++i) { const int ct = 2 * cp + i; f32x4 cA = {0.f, 0.f, 0.f, 0.f}, sA = cA, cB = cA, sB = cA;
; #pragma unroll
;             for (int kk = 0; kk < 2; ++kk) {
;                 const LAS unsigned char* ad = D + (kk * 32 + 8 * l4 + q) * 144 + (ct * 16 + 4 * pp) * 2;
;                 const s16x4 lo = vtr(ad), hi = vtr(ad + 4 * 144); const bf16x8 af = __builtin_shufflevector(lo, hi, 0, 1, 2, 3, 4, 5, 6, 7);
;                 cA = mfma16(af, mcs[kk], cA); sA = mfma16(af, msn[kk], sA);
;                 const LAS unsigned char* bd = ad + 64 * 144;
;                 const s16x4 lo2 = vtr(bd), hi2 = vtr(bd + 4 * 144); const bf16x8 bf_ = __builtin_shufflevector(lo2, hi2, 0, 1, 2, 3, 4, 5, 6, 7);
;                 cB = mfma16(bf_, mcs[kk], cB); sB = mfma16(bf_, msn[kk], sB); }
;             f32x4 sre = cA + sB, sim = cB - sA;
;             if (mb == 0 && ct == 0 && l4 == 0) { sre[0] = cA[0]; sim[0] = -sA[0];
;                 *(GAS unsigned short*)(Tb + 256) = (unsigned short)pk2(cB[0], 0.f); *(GAS unsigned short*)(Tb + 512 + 256) = (unsigned short)pk2(-sB[0], 0.f); }
;             const int ch = ct * 16 + 4 * l4; v2u p;
;             p.x = pk2(sre[0], sre[1]); p.y = pk2(sre[2], sre[3]); *(GAS v2u*)(Tb + ch) = p;
;             p.x = pk2(sim[0], sim[1]); p.y = pk2(sim[2], sim[3]); *(GAS v2u*)(Tb + 512 + ch) = p; }
.LBB0_361:
	s_bitcmp1_b32 s20, 0
	s_cselect_b32 s25, 0x4800, 0
	s_add_i32 s4, s15, s20
	s_mov_b32 s5, s24
	s_add_i32 s10, s4, 1
	s_add_i32 s24, s24, 4
	s_and_b32 s27, s24, 0xfffff000
	s_bfe_u32 s10, s10, 0x60004
	s_or_b32 s10, s27, s10
	s_ashr_i32 s27, s10, 31
	v_mov_b32_e32 v21, s27
	v_or_b32_e32 v20, s10, v52
	v_lshlrev_b64 v[20:21], 12, v[20:21]
	s_and_b32 s10, s21, 0x600
	v_lshl_add_u64 v[20:21], s[76:77], 0, v[20:21]
	s_lshl_b32 s10, s10, 1
	v_lshl_add_u64 v[20:21], v[20:21], 0, s[10:11]
	s_and_b32 s10, s22, 0xc0
	s_lshl_b32 s10, s10, 1
	v_lshl_add_u64 v[20:21], v[20:21], 0, s[10:11]
	v_lshl_add_u64 v[24:25], v[20:21], 0, v[2:3]
	v_lshl_add_u64 v[20:21], v[54:55], 1, v[24:25]
	v_lshl_add_u64 v[24:25], v[56:57], 1, v[24:25]
	global_load_dwordx4 v[20:23], v[20:21], off
	s_bfe_u32 s10, s4, 0x60004
	global_load_dwordx4 v[24:27], v[24:25], off
	s_and_b32 s5, s5, 0xfffff000
	s_or_b32 s5, s5, s10
	s_ashr_i32 s10, s5, 31
	v_mov_b32_e32 v29, s10
	v_or_b32_e32 v28, s5, v48
	v_lshlrev_b64 v[28:29], 13, v[28:29]
	s_and_b32 s5, s23, 0xc00
	s_and_b32 s4, s20, 3
	v_lshl_add_u64 v[28:29], s[0:1], 0, v[28:29]
	s_lshl_b32 s10, s5, 1
	v_add_u32_e32 v71, s25, v66
	v_lshl_add_u64 v[28:29], v[28:29], 0, s[10:11]
	s_lshl_b32 s10, s4, 7
	v_add3_u32 v44, v71, s7, v65
	v_lshl_add_u64 v[62:63], v[28:29], 0, s[10:11]
	ds_read_b64_tr_b16 v[28:29], v44
	ds_read_b64_tr_b16 v[30:31], v44 offset:576
	s_waitcnt lgkmcnt(0)
	v_mfma_f32_16x16x32_bf16 v[32:35], v[28:31], v[12:15], 0
	s_or_b32 s4, s4, s6
	s_cmp_eq_u32 s4, 0
	s_cselect_b64 s[4:5], -1, 0
	v_mfma_f32_16x16x32_bf16 v[36:39], v[28:31], v[16:19], 0
	ds_read_b64_tr_b16 v[28:29], v44 offset:9216
	ds_read_b64_tr_b16 v[30:31], v44 offset:9792
	ds_read_b64_tr_b16 v[76:77], v44 offset:4608
	ds_read_b64_tr_b16 v[78:79], v44 offset:5184
	s_and_b64 s[28:29], s[40:41], s[4:5]
	s_waitcnt lgkmcnt(2)
	v_mfma_f32_16x16x32_bf16 v[40:43], v[28:31], v[12:15], 0
	v_mfma_f32_16x16x32_bf16 v[72:75], v[28:31], v[16:19], 0
	s_waitcnt lgkmcnt(0)
	v_mfma_f32_16x16x32_bf16 v[28:31], v[76:79], v[4:7], v[32:35]
	v_mfma_f32_16x16x32_bf16 v[32:35], v[76:79], v[8:11], v[36:39]
	ds_read_b64_tr_b16 v[76:77], v44 offset:13824
	ds_read_b64_tr_b16 v[78:79], v44 offset:14400
	s_waitcnt lgkmcnt(0)
	v_mfma_f32_16x16x32_bf16 v[36:39], v[76:79], v[4:7], v[40:43]
	v_mfma_f32_16x16x32_bf16 v[40:43], v[76:79], v[8:11], v[72:75]
	s_nop 6
	v_sub_f32_e32 v35, v39, v35
	v_sub_f32_e32 v34, v38, v34
	v_sub_f32_e32 v33, v37, v33
	v_sub_f32_e32 v38, v36, v32
	v_pk_add_f32 v[44:45], v[30:31], v[42:43]
	v_pk_add_f32 v[42:43], v[28:29], v[40:41]
	s_and_saveexec_b64 s[4:5], s[28:29]
	s_cbranch_execz .LBB0_360
	v_mov_b32_e32 v30, v44
	v_mov_b32_e32 v31, v45
	v_mov_b32_e32 v29, v43
	v_mov_b64_e32 v[44:45], v[30:31]
	v_xor_b32_e32 v38, 0x80000000, v32
	v_cvt_pk_bf16_f32 v32, v36, v37
	v_mov_b64_e32 v[42:43], v[28:29]
	v_cvt_pk_bf16_f32 v36, -v40, s0
	global_store_short v[62:63], v32, off offset:512
	global_store_short v[62:63], v36, off offset:1536
	s_branch .LBB0_360

; #define GAS __attribute__((address_space(1)))
; #define LAS __attribute__((address_space(3)))
;     constexpr int NK = 128, TPW = NM / 32, TILE = NK * 144;
;     const int l15 = F.lane & 15, l4 = F.lane >> 4, q = l15 >> 2, pp = l15 & 3;
;     const int mt = (F.wave * TPW) >> 2;
;     bf16x8 mx[4];
; #pragma unroll
;     for (int kk = 0; kk < 4; ++kk) mx[kk] = ld_frag_g(Mx + (size_t)(mt * 16 + l15) * NK + kk * 32 + 8 * l4);
;     v4u pre[2];
;     { const auto ri = spec.rin(u0);
; #pragma unroll
;       for (int i = 0; i < 2; ++i) { const int p = F.tid + 512 * i; pre[i] = *(const GAS v4u*)(ri(p >> 3) + (p & 7) * 8); } }
; #pragma unroll
;     for (int i = 0; i < 2; ++i) { const int p = F.tid + 512 * i; *(LAS v4u*)(F.lds + (p >> 3) * 144 + (p & 7) * 16) = pre[i]; }
;     __syncthreads();
.LBB0_420:
	s_mul_i32 s14, s9, 10
	s_mul_hi_i32 s5, s14, 0x66666667
	s_lshr_b32 s6, s5, 31
	s_ashr_i32 s5, s5, 9
	s_add_i32 s5, s5, s6
	s_mulk_i32 s5, 0x500
	s_sub_i32 s5, s14, s5
	s_sext_i32_i16 s6, s5
	s_mulk_i32 s6, 0x6667
	s_lshr_b32 s7, s6, 31
	s_ashr_i32 s6, s6, 19
	s_add_i32 s6, s6, s7
	s_mul_i32 s7, s6, 20
	s_sub_i32 s7, s5, s7
	s_mulk_i32 s7, 0x67
	s_sext_i32_i16 s15, s7
	s_ashr_i32 s15, s15, 9
	s_bfe_u32 s7, s7, 0x1000f
	s_add_i32 s15, s15, s7
	s_sext_i32_i16 s7, s15
	s_mul_i32 s15, s5, 0x6667
	s_ashr_i32 s4, s9, 31
	s_lshr_b32 s16, s15, 31
	s_ashr_i32 s15, s15, 17
	s_lshr_b32 s4, s4, 25
	s_add_i32 s15, s15, s16
	s_add_i32 s4, s9, s4
	s_mul_i32 s15, s15, 5
	s_sub_i32 s5, s5, s15
	s_lshl_b32 s4, s4, 5
	s_sext_i32_i16 s15, s5
	s_and_b32 s4, s4, 0xfffff000
	s_lshl_b32 s5, s6, 6
	s_add_i32 s4, s5, s4
	s_ashr_i32 s5, s4, 31
	s_lshl_b64 s[4:5], s[4:5], 13
	s_add_u32 s6, s10, s4
	s_addc_u32 s16, s12, s5
	s_lshl_b32 s4, s7, 10
	s_ashr_i32 s5, s4, 31
	s_lshl_b64 s[4:5], s[4:5], 1
	s_add_u32 s6, s6, s4
	s_addc_u32 s7, s16, s5
	s_lshl_b32 s4, s15, 6
	s_ashr_i32 s5, s4, 31
	s_lshl_b64 s[4:5], s[4:5], 1
	s_add_u32 s4, s6, s4
	s_addc_u32 s5, s7, s5
	v_lshl_add_u64 v[4:5], s[4:5], 0, v[2:3]
	v_mov_b32_e32 v41, v3
	v_lshl_add_u64 v[4:5], v[4:5], 0, v[40:41]
	v_lshl_add_u64 v[4:5], v[34:35], 1, v[4:5]
	global_load_dwordx4 v[20:23], v[4:5], off
	global_load_dwordx4 v[24:27], v[4:5], off offset:1024
	global_load_dwordx4 v[16:19], v[32:33], off
	global_load_dwordx4 v[12:15], v[32:33], off offset:64
	global_load_dwordx4 v[8:11], v[32:33], off offset:128
	s_nop 0
	global_load_dwordx4 v[4:7], v[32:33], off offset:192
	s_mov_b32 s15, 0
	s_waitcnt vmcnt(5)
	ds_write_b128 v58, v[20:23]
	s_waitcnt vmcnt(4)
	ds_write_b128 v59, v[24:27]
	s_waitcnt vmcnt(0) lgkmcnt(0)
	s_barrier
	s_branch .LBB0_423

; #define GAS __attribute__((address_space(1)))
; #define LAS __attribute__((address_space(3)))
; DI s16x4 vtr(const LAS unsigned char* p) { return __builtin_bit_cast(s16x4, __builtin_amdgcn_ds_read_tr16_b64_v4i16((LAS s16x4*)p)); }
; DI f32x4 mfma16(bf16x8 a, bf16x8 b, f32x4 c) { return __builtin_amdgcn_mfma_f32_16x16x32_bf16(a, b, c, 0, 0, 0); }
;     ...
;     for (int k = 0; k < NU; ++k) {
;         LAS unsigned char* D = F.lds + (k & 1) * TILE;
;         if (k + 1 < NU) { const auto ri = spec.rin(u0 + k + 1);
; #pragma unroll
;             for (int i = 0; i < 2; ++i) { const int p = F.tid + 512 * i; pre[i] = *(const GAS v4u*)(ri(p >> 3) + (p & 7) * 8); } }
;         const auto st = spec.sto(u0 + k);
; #pragma unroll
;         for (int i = 0; i < TPW; ++i) { const int ct = (F.wave * TPW + i) & 3; f32x4 acc = {0.f, 0.f, 0.f, 0.f};
; #pragma unroll
;             for (int kk = 0; kk < 4; ++kk) {
;                 const LAS unsigned char* ad = D + (kk * 32 + 8 * l4 + q) * 144 + (ct * 16 + 4 * pp) * 2;
;                 const s16x4 lo = vtr(ad), hi = vtr(ad + 4 * 144);
;                 acc = mfma16(__builtin_shufflevector(lo, hi, 0, 1, 2, 3, 4, 5, 6, 7), mx[kk], acc); }
;             st(mt * 16 + l15, ct * 16 + 4 * l4, acc); }
;         if (k + 1 < NU) { LAS unsigned char* Dn = F.lds + ((k + 1) & 1) * TILE;
; #pragma unroll
;             for (int i = 0; i < 2; ++i) { const int p = F.tid + 512 * i; *(LAS v4u*)(Dn + (p >> 3) * 144 + (p & 7) * 16) = pre[i]; } }
;         __syncthreads();
.LBB0_422:
	s_add_i32 s15, s15, 1
	s_bitcmp1_b32 s15, 0
	s_cselect_b32 s4, 0x4800, 0
	s_add_i32 s4, s4, 0
	s_nop 0
	v_add3_u32 v28, s4, v50, v51
	s_and_b32 s5, s17, 0xffff
	s_cmp_eq_u32 s5, 4
	s_cbranch_scc1 .Ls2_slow
	s_waitcnt vmcnt(5)
	ds_write_b128 v28, v[24:27]
	v_add3_u32 v24, s4, v52, v51
	s_waitcnt vmcnt(4)
	s_branch .Ls2_join
.Ls2_slow:
	s_waitcnt vmcnt(1)
	ds_write_b128 v28, v[24:27]
	v_add3_u32 v24, s4, v52, v51
	s_waitcnt vmcnt(0)
.Ls2_join:
	s_cmp_eq_u32 s15, 9
	ds_write_b128 v24, v[20:23]
	s_waitcnt lgkmcnt(0)
	s_barrier
	s_cbranch_scc1 .LBB0_442
.LBB0_423:
	s_bitcmp1_b32 s15, 0
	s_cselect_b32 s6, 0x4800, 0
	s_add_i32 s7, s13, s15
	s_add_i32 s4, s7, 1
	s_mul_hi_i32 s5, s4, 0x66666667
	s_lshr_b32 s16, s5, 31
	s_ashr_i32 s5, s5, 9
	s_add_i32 s5, s5, s16
	s_mul_i32 s16, s5, 0x500
	s_sub_i32 s4, s4, s16
	s_mul_i32 s16, s4, 0x6667
	s_ashr_i32 s17, s16, 19
	s_lshr_b32 s18, s16, 31
	s_ashr_i32 s16, s16, 17
	s_add_i32 s17, s17, s18
	s_add_i32 s16, s16, s18
	s_mul_i32 s19, s17, 20
	s_mul_i32 s16, s16, 5
	s_sub_i32 s19, s4, s19
	s_sub_i32 s4, s4, s16
	s_mulk_i32 s19, 0x67
	s_sext_i32_i16 s16, s4
	s_lshl_b32 s4, s5, 12
	s_lshl_b32 s5, s17, 6
	s_sext_i32_i16 s20, s19
	s_add_i32 s4, s5, s4
	s_ashr_i32 s20, s20, 9
	s_bfe_u32 s19, s19, 0x1000f
	s_ashr_i32 s5, s4, 31
	s_add_i32 s20, s20, s19
	s_lshl_b64 s[4:5], s[4:5], 13
	s_sext_i32_i16 s19, s20
	s_add_u32 s17, s10, s4
	s_addc_u32 s18, s12, s5
	s_lshl_b32 s4, s19, 10
	s_ashr_i32 s5, s4, 31
	s_lshl_b64 s[4:5], s[4:5], 1
	s_add_u32 s17, s17, s4
	s_addc_u32 s18, s18, s5
	s_lshl_b32 s4, s16, 6
	s_ashr_i32 s5, s4, 31
	s_lshl_b64 s[4:5], s[4:5], 1
	s_add_u32 s4, s17, s4
	s_addc_u32 s5, s18, s5
	v_lshl_add_u64 v[20:21], s[4:5], 0, v[2:3]
	v_lshl_add_u64 v[20:21], v[20:21], 0, v[40:41]
	v_lshl_add_u64 v[20:21], v[34:35], 1, v[20:21]
	global_load_dwordx4 v[24:27], v[20:21], off
	s_nop 0
	global_load_dwordx4 v[20:23], v[20:21], off offset:1024
	s_mul_hi_i32 s4, s7, 0x66666667
	s_lshr_b32 s5, s4, 31
	s_ashr_i32 s4, s4, 9
	s_add_i32 s4, s4, s5
	s_mul_i32 s5, s4, 0x500
	s_sub_i32 s5, s7, s5
	s_mul_i32 s7, s5, 0x6667
	s_ashr_i32 s16, s7, 19
	s_lshr_b32 s17, s7, 31
	s_add_i32 s18, s16, s17
	s_mul_i32 s16, s18, 20
	s_sub_i32 s16, s5, s16
	s_mulk_i32 s16, 0x67
	s_sext_i32_i16 s19, s16
	s_ashr_i32 s19, s19, 9
	s_bfe_u32 s16, s16, 0x1000f
	s_add_i32 s19, s19, s16
	s_ashr_i32 s7, s7, 17
	v_add_u32_e32 v30, s18, v53
	s_lshl_b32 s20, s4, 12
	s_sext_i32_i16 s19, s19
	s_add_i32 s7, s7, s17
	v_add_u32_e32 v28, s20, v30
	s_mul_i32 s7, s7, 5
	v_ashrrev_i32_e32 v29, 31, v28
	s_lshl_b32 s4, s19, 9
	s_sub_i32 s17, s5, s7
	v_lshlrev_b64 v[28:29], 12, v[28:29]
	s_ashr_i32 s5, s4, 31
	v_add_u32_e32 v62, s6, v55
	v_lshl_add_u64 v[28:29], s[0:1], 0, v[28:29]
	s_lshl_b64 s[6:7], s[4:5], 1
	v_lshl_add_u64 v[42:43], v[28:29], 0, s[6:7]
	s_and_b32 s4, s17, 0xffff
	v_sub_u32_e32 v28, 0, v30
	s_cmp_lg_u32 s4, 4
	v_and_b32_e32 v28, 0xfff, v28
	s_sext_i32_i16 s16, s17
	s_cselect_b64 s[4:5], -1, 0
	s_add_u32 s6, s0, s6
	v_or_b32_e32 v28, s20, v28
	s_addc_u32 s7, s1, s7
	s_lshl_b32 s18, s16, 6
	v_ashrrev_i32_e32 v29, 31, v28
	s_ashr_i32 s19, s18, 31
	v_lshlrev_b64 v[28:29], 12, v[28:29]
	s_lshl_b64 s[18:19], s[18:19], 1
	v_lshl_add_u64 v[28:29], s[6:7], 0, v[28:29]
	v_add3_u32 v48, v62, v56, v54
	v_lshl_add_u64 v[46:47], v[28:29], 0, s[18:19]
	ds_read_b64_tr_b16 v[28:29], v48
	ds_read_b64_tr_b16 v[30:31], v48 offset:576
	ds_read_b64_tr_b16 v[64:65], v48 offset:4608
	ds_read_b64_tr_b16 v[66:67], v48 offset:5184
	s_waitcnt lgkmcnt(2)
	v_mfma_f32_16x16x32_bf16 v[28:31], v[28:31], v[16:19], 0
	v_lshl_add_u64 v[44:45], v[42:43], 0, s[18:19]
	s_mov_b64 s[6:7], -1
	s_and_b64 vcc, exec, s[4:5]
	s_waitcnt lgkmcnt(0)
	v_mfma_f32_16x16x32_bf16 v[28:31], v[64:67], v[12:15], v[28:31]
	ds_read_b64_tr_b16 v[64:65], v48 offset:9216
	ds_read_b64_tr_b16 v[66:67], v48 offset:9792
	s_waitcnt lgkmcnt(0)
	v_mfma_f32_16x16x32_bf16 v[28:31], v[64:67], v[8:11], v[28:31]
	ds_read_b64_tr_b16 v[64:65], v48 offset:13824
	ds_read_b64_tr_b16 v[66:67], v48 offset:14400
	s_waitcnt lgkmcnt(0)
	v_mfma_f32_16x16x32_bf16 v[28:31], v[64:67], v[4:7], v[28:31]
	s_cbranch_vccz .LBB0_429
	s_nop 6
	v_pk_mul_f32 v[48:49], v[28:29], s[86:87] op_sel_hi:[1,0]
	v_pk_mul_f32 v[30:31], v[30:31], s[86:87] op_sel_hi:[1,0]
	v_cvt_pk_bf16_f32 v48, v48, v49
	v_cvt_pk_bf16_f32 v49, v30, v31
	v_lshlrev_b64 v[30:31], 1, v[36:37]
	v_or_b32_e32 v29, s16, v36
	v_lshl_add_u64 v[64:65], v[44:45], 0, v[30:31]
	v_lshl_add_u64 v[30:31], v[46:47], 0, v[30:31]
	v_cmp_ne_u32_e32 vcc, 0, v29
	global_store_dwordx2 v[64:65], v[48:49], off
	s_and_saveexec_b64 s[6:7], vcc
	s_xor_b64 s[6:7], exec, s[6:7]
	s_cbranch_execz .LBB0_426
	global_store_dwordx2 v[30:31], v[48:49], off offset:512
